# xcd barrier at P0-P1 seam; P7 mid() ssq loads batched under one wait; norm phases P1/P4 rows interleaved across the 8 waves
# speedup vs baseline: 1.0209x; 1.0209x over previous
.Lgs0_238:
	s_or_b64 exec, exec, s[0:1]
	s_add_u32 s86, s66, 0x200000
	s_addc_u32 s87, s67, 0
	s_lshl_b32 s0, s2, 8
	s_mov_b32 s1, s90
	s_add_i32 s20, s1, s0
	s_cmp_lt_i32 s20, 0x10000
	s_cselect_b64 s[10:11], -1, 0
	s_lshl_b32 s24, s64, 8
	v_mov_b32_e32 v0, v210
	s_and_b64 vcc, exec, s[10:11]
	v_mbcnt_lo_u32_b32 v208, -1, 0
	s_waitcnt lgkmcnt(0)
	s_barrier
	s_cbranch_vccz .LBB0_185
	v_lshlrev_b32_e32 v1, 2, v0
	v_and_b32_e32 v2, 0xfc, v1
	v_mbcnt_hi_u32_b32 v1, -1, v208
	v_and_b32_e32 v3, 64, v1
	v_add_u32_e32 v3, 64, v3
	v_xor_b32_e32 v6, 1, v1
	v_cmp_lt_i32_e32 vcc, v6, v3
	s_ashr_i32 s21, s20, 31
	s_lshl_b64 s[0:1], s[20:21], 11
	v_cndmask_b32_e32 v6, v1, v6, vcc
	v_lshlrev_b32_e32 v72, 2, v6
	v_xor_b32_e32 v6, 2, v1
	v_cmp_lt_i32_e32 vcc, v6, v3
	v_mov_b32_e32 v5, 0
	v_lshlrev_b32_e32 v4, 2, v2
	v_cndmask_b32_e32 v6, v1, v6, vcc
	v_lshlrev_b32_e32 v73, 2, v6
	v_xor_b32_e32 v6, 4, v1
	v_cmp_lt_i32_e32 vcc, v6, v3
	v_and_b32_e32 v0, 63, v0
	s_add_u32 s0, s66, s0
	v_cndmask_b32_e32 v6, v1, v6, vcc
	v_lshlrev_b32_e32 v74, 2, v6
	v_xor_b32_e32 v6, 8, v1
	v_cmp_lt_i32_e32 vcc, v6, v3
	v_lshl_add_u64 v[48:49], s[8:9], 0, v[4:5]
	v_lshl_add_u64 v[50:51], s[16:17], 0, v[4:5]
	v_cndmask_b32_e32 v6, v1, v6, vcc
	v_lshlrev_b32_e32 v75, 2, v6
	v_xor_b32_e32 v6, 16, v1
	v_cmp_lt_i32_e32 vcc, v6, v3
	v_lshlrev_b32_e32 v4, 3, v0
	s_addc_u32 s1, s67, s1
	v_cndmask_b32_e32 v6, v1, v6, vcc
	v_lshlrev_b32_e32 v76, 2, v6
	v_xor_b32_e32 v6, 32, v1
	v_cmp_lt_i32_e32 vcc, v6, v3
	v_or_b32_e32 v8, 0x200, v2
	v_or_b32_e32 v10, 0x300, v2
	v_cndmask_b32_e32 v1, v1, v6, vcc
	v_lshlrev_b32_e32 v77, 2, v1
	v_or_b32_e32 v6, 0x100, v2
	v_lshl_add_u64 v[0:1], s[0:1], 0, v[4:5]
	s_mov_b64 s[0:1], 0x4000400
	s_ashr_i32 s25, s24, 31
	v_lshl_add_u64 v[52:53], v[0:1], 0, s[0:1]
	s_lshl_b64 s[4:5], s[24:25], 11
	v_lshlrev_b32_e32 v78, 2, v2
	v_lshlrev_b32_e32 v79, 2, v6
	v_lshlrev_b32_e32 v80, 2, v8
	v_lshlrev_b32_e32 v81, 2, v10
	v_mov_b32_e32 v82, 0x358637bd
	s_mov_b32 s3, 0xf800000
	v_mov_b32_e32 v83, 0x260
	s_movk_i32 s18, 0x7fff
	s_mov_b32 s19, 0xffff0000
	s_mov_b64 s[6:7], 0x4000
	s_mov_b32 s12, s20
	s_branch .LBB0_181

.LBB0_181:
	s_ashr_i32 s13, s12, 31
	s_lshr_b32 s0, s13, 21
	s_add_i32 s0, s12, s0
	s_ashr_i32 s0, s0, 11
	s_mul_hi_i32 s1, s0, 0x9000
	s_mul_i32 s0, s0, 0x9000
	s_add_u32 s0, s86, s0
	s_addc_u32 s1, s87, s1
	s_add_u32 s14, s0, 0x1000
	s_addc_u32 s15, s1, 0
	global_load_dwordx4 v[28:31], v78, s[14:15]
	global_load_dwordx4 v[32:35], v79, s[14:15]
	global_load_dwordx4 v[36:39], v[50:51], off
	global_load_dwordx4 v[40:43], v[50:51], off offset:1024
	global_load_dwordx4 v[56:59], v80, s[14:15]
	global_load_dwordx4 v[60:63], v81, s[14:15]
	global_load_dwordx4 v[0:3], v78, s[0:1]
	global_load_dwordx4 v[4:7], v78, s[0:1] offset:1024
	global_load_dwordx4 v[66:69], v[50:51], off offset:2048
	global_load_dwordx4 v[84:87], v[50:51], off offset:3072
	global_load_dwordx4 v[8:11], v78, s[0:1] offset:2048
	global_load_dwordx4 v[12:15], v78, s[0:1] offset:3072
	s_lshl_b64 s[0:1], s[12:13], 12
	v_lshl_add_u64 v[54:55], v[48:49], 0, s[0:1]
	global_load_dwordx4 v[44:47], v[54:55], off
	global_load_dwordx4 v[24:27], v[54:55], off offset:1024
	global_load_dwordx4 v[20:23], v[54:55], off offset:2048
	global_load_dwordx4 v[16:19], v[54:55], off offset:3072
	v_mov_b64_e32 v[54:55], v[52:53]
	s_add_i32 s13, s12, 0xf8
	s_mov_b32 s14, s12
	s_waitcnt vmcnt(15)
	v_pk_add_f32 v[30:31], v[30:31], 1.0 op_sel_hi:[1,0]
	v_pk_add_f32 v[28:29], v[28:29], 1.0 op_sel_hi:[1,0]
	s_waitcnt vmcnt(14)
	v_pk_add_f32 v[34:35], v[34:35], 1.0 op_sel_hi:[1,0]
	v_pk_add_f32 v[32:33], v[32:33], 1.0 op_sel_hi:[1,0]
	s_waitcnt vmcnt(11)
	v_pk_add_f32 v[64:65], v[58:59], 1.0 op_sel_hi:[1,0]
	v_pk_add_f32 v[70:71], v[56:57], 1.0 op_sel_hi:[1,0]
	s_waitcnt vmcnt(10)
	v_pk_add_f32 v[88:89], v[62:63], 1.0 op_sel_hi:[1,0]
	v_pk_add_f32 v[90:91], v[60:61], 1.0 op_sel_hi:[1,0]
	v_pk_mul_f32 v[56:57], v[38:39], v[30:31]
	v_pk_mul_f32 v[58:59], v[36:37], v[28:29]
	v_pk_mul_f32 v[60:61], v[42:43], v[34:35]
	v_pk_mul_f32 v[62:63], v[40:41], v[32:33]
	s_waitcnt vmcnt(7)
	v_pk_mul_f32 v[64:65], v[68:69], v[64:65]
	v_pk_mul_f32 v[66:67], v[66:67], v[70:71]
	s_waitcnt vmcnt(6)
	v_pk_mul_f32 v[68:69], v[86:87], v[88:89]
	v_pk_mul_f32 v[70:71], v[84:85], v[90:91]
	s_branch .LBB0_183

.LBB0_183:
	s_mov_b32 s0, s14
	s_add_i32 s14, s14, 8
	s_cmp_ge_i32 s0, s13
	s_cselect_b64 s[16:17], -1, 0
	s_cmp_lt_i32 s0, s13
	s_waitcnt vmcnt(3)
	v_mov_b32_e32 v28, v44
	v_mov_b32_e32 v29, v45
	v_mov_b32_e32 v30, v46
	v_mov_b32_e32 v31, v47
	s_waitcnt vmcnt(2)
	v_mov_b32_e32 v32, v24
	v_mov_b32_e32 v33, v25
	v_mov_b32_e32 v34, v26
	v_mov_b32_e32 v35, v27
	s_waitcnt vmcnt(1)
	v_mov_b32_e32 v36, v20
	v_mov_b32_e32 v37, v21
	v_mov_b32_e32 v38, v22
	v_mov_b32_e32 v39, v23
	s_waitcnt vmcnt(0)
	v_mov_b32_e32 v40, v16
	v_mov_b32_e32 v41, v17
	v_mov_b32_e32 v42, v18
	v_mov_b32_e32 v43, v19
	s_cbranch_scc0 .LBB0_182
	s_ashr_i32 s15, s14, 31
	s_lshl_b64 s[0:1], s[14:15], 12
	v_lshl_add_u64 v[84:85], v[48:49], 0, s[0:1]
	global_load_dwordx4 v[28:31], v[84:85], off
	global_load_dwordx4 v[32:35], v[84:85], off offset:1024
	global_load_dwordx4 v[36:39], v[84:85], off offset:2048
	global_load_dwordx4 v[40:43], v[84:85], off offset:3072
	s_branch .LBB0_182

.LBB0_397:
	s_or_b64 exec, exec, s[0:1]
	s_andn2_b64 vcc, exec, s[10:11]
	s_waitcnt lgkmcnt(0)
	s_barrier
	s_cbranch_vccnz .LBB0_406
	v_mbcnt_hi_u32_b32 v2, -1, v208
	v_and_b32_e32 v3, 64, v2
	v_add_u32_e32 v3, 64, v3
	v_xor_b32_e32 v4, 1, v2
	v_cmp_lt_i32_e32 vcc, v4, v3
	v_and_b32_e32 v131, 63, v0
	v_mov_b32_e32 v129, 0
	v_cndmask_b32_e32 v4, v2, v4, vcc
	v_lshlrev_b32_e32 v209, 2, v4
	v_xor_b32_e32 v4, 2, v2
	v_cmp_lt_i32_e32 vcc, v4, v3
	v_lshlrev_b32_e32 v0, 4, v131
	v_mov_b32_e32 v1, v129
	v_cndmask_b32_e32 v4, v2, v4, vcc
	v_lshlrev_b32_e32 v211, 2, v4
	v_xor_b32_e32 v4, 4, v2
	v_cmp_lt_i32_e32 vcc, v4, v3
	v_add_u32_e32 v124, 0, v0
	v_lshl_add_u64 v[176:177], s[62:63], 0, v[0:1]
	v_cndmask_b32_e32 v4, v2, v4, vcc
	v_lshlrev_b32_e32 v212, 2, v4
	v_xor_b32_e32 v4, 8, v2
	v_cmp_lt_i32_e32 vcc, v4, v3
	v_lshl_add_u64 v[180:181], s[22:23], 0, v[0:1]
	s_ashr_i32 s21, s20, 31
	v_cndmask_b32_e32 v4, v2, v4, vcc
	v_lshlrev_b32_e32 v213, 2, v4
	v_xor_b32_e32 v4, 16, v2
	v_cmp_lt_i32_e32 vcc, v4, v3
	s_lshl_b64 s[0:1], s[20:21], 5
	s_add_u32 s0, s66, s0
	v_cndmask_b32_e32 v4, v2, v4, vcc
	v_lshlrev_b32_e32 v214, 2, v4
	v_xor_b32_e32 v4, 32, v2
	v_cmp_lt_i32_e32 vcc, v4, v3
	v_lshlrev_b32_e32 v128, 2, v131
	s_addc_u32 s1, s67, s1
	v_cndmask_b32_e32 v2, v2, v4, vcc
	v_lshlrev_b32_e32 v215, 2, v2
	ds_read_b128 v[0:3], v124
	ds_read_b128 v[4:7], v124 offset:1024
	ds_read_b128 v[8:11], v124 offset:2048
	ds_read_b128 v[12:15], v124 offset:3072
	ds_read_b128 v[16:19], v124 offset:4096
	ds_read_b128 v[20:23], v124 offset:5120
	ds_read_b128 v[24:27], v124 offset:6144
	ds_read_b128 v[28:31], v124 offset:7168
	ds_read_b128 v[32:35], v124 offset:8192
	ds_read_b128 v[36:39], v124 offset:9216
	ds_read_b128 v[40:43], v124 offset:10240
	ds_read_b128 v[44:47], v124 offset:11264
	ds_read_b128 v[48:51], v124 offset:12288
	ds_read_b128 v[52:55], v124 offset:13312
	ds_read_b128 v[56:59], v124 offset:14336
	ds_read_b128 v[60:63], v124 offset:15360
	ds_read_b128 v[64:67], v124 offset:16384
	ds_read_b128 v[68:71], v124 offset:17408
	ds_read_b128 v[72:75], v124 offset:18432
	ds_read_b128 v[76:79], v124 offset:19456
	ds_read_b128 v[80:83], v124 offset:20480
	ds_read_b128 v[84:87], v124 offset:21504
	ds_read_b128 v[88:91], v124 offset:22528
	ds_read_b128 v[92:95], v124 offset:23552
	ds_read_b128 v[96:99], v124 offset:24576
	ds_read_b128 v[100:103], v124 offset:25600
	ds_read_b128 v[104:107], v124 offset:26624
	ds_read_b128 v[108:111], v124 offset:27648
	ds_read_b128 v[112:115], v124 offset:28672
	ds_read_b128 v[116:119], v124 offset:29696
	ds_read_b128 v[120:123], v124 offset:30720
	ds_read_b128 v[124:127], v124 offset:31744
	v_lshl_add_u64 v[136:137], s[0:1], 0, v[128:129]
	s_mov_b64 s[0:1], 0x500000
	s_ashr_i32 s25, s24, 31
	v_lshl_add_u64 v[182:183], v[136:137], 0, s[0:1]
	s_lshl_b64 s[22:23], s[24:25], 5
	s_lshl_b64 s[0:1], s[20:21], 11
	s_add_u32 s0, s66, s0
	v_lshlrev_b32_e32 v136, 3, v131
	v_mov_b32_e32 v137, v129
	s_addc_u32 s1, s67, s1
	v_or_b32_e32 v130, 0x100, v128
	v_or_b32_e32 v132, 0x200, v128
	v_or_b32_e32 v134, 0x300, v128
	v_lshl_add_u64 v[136:137], s[0:1], 0, v[136:137]
	s_mov_b64 s[0:1], 0x4000400
	v_cmp_gt_u32_e64 s[4:5], 8, v131
	v_lshl_add_u64 v[178:179], s[42:43], 0, v[128:129]
	v_cmp_eq_u32_e64 s[6:7], 7, v131
	v_cmp_eq_u32_e64 s[8:9], 6, v131
	v_cmp_eq_u32_e64 s[10:11], 5, v131
	v_cmp_eq_u32_e64 s[12:13], 4, v131
	v_cmp_eq_u32_e64 s[14:15], 3, v131
	v_cmp_eq_u32_e64 s[16:17], 2, v131
	v_cmp_eq_u32_e64 s[18:19], 1, v131
	v_lshl_add_u64 v[184:185], v[136:137], 0, s[0:1]
	s_lshl_b64 s[26:27], s[24:25], 11
	v_lshlrev_b32_e32 v216, 2, v128
	v_lshlrev_b32_e32 v217, 2, v130
	v_lshlrev_b32_e32 v218, 2, v132
	v_lshlrev_b32_e32 v219, 2, v134
	v_mov_b32_e32 v220, 0x358637bd
	s_mov_b32 s25, 0xf800000
	v_mov_b32_e32 v221, 0x260
	s_movk_i32 s42, 0x7fff
	s_mov_b32 s43, 0xffff0000
	s_mov_b32 s48, 0xbfb8aa3b
	s_mov_b32 s49, 0x800000
	s_mov_b32 s52, 0x3f317217
	s_mov_b32 s53, 0x7f800000
	s_mov_b64 s[28:29], 0x4000
	s_mov_b64 s[100:101], 0x100
	v_mov_b32_e32 v222, 0x41b17218
	s_branch .LBB0_400

.LBB0_400:
	s_ashr_i32 s21, s20, 31
	s_lshr_b32 s0, s21, 21
	s_add_i32 s0, s20, s0
	s_ashr_i32 s0, s0, 11
	s_mul_hi_i32 s1, s0, 0x9000
	s_mul_i32 s0, s0, 0x9000
	s_add_u32 s30, s86, s0
	s_addc_u32 s31, s87, s1
	s_add_u32 s0, s30, 0x4000
	s_addc_u32 s1, s31, 0
	global_load_dwordx4 v[144:147], v216, s[0:1]
	global_load_dwordx4 v[148:151], v217, s[0:1]
	global_load_dwordx4 v[152:155], v218, s[0:1]
	global_load_dwordx4 v[156:159], v[180:181], off
	global_load_dwordx4 v[196:199], v[180:181], off offset:1024
	global_load_dwordx4 v[190:193], v219, s[0:1]
	global_load_dwordx4 v[200:203], v[180:181], off offset:2048
	global_load_dwordx4 v[204:207], v[180:181], off offset:3072
	s_add_u32 s0, s30, 0x3000
	s_addc_u32 s1, s31, 0
	s_lshl_b64 s[30:31], s[20:21], 12
	v_lshl_add_u64 v[136:137], v[176:177], 0, s[30:31]
	global_load_dwordx4 v[128:131], v216, s[0:1]
	global_load_dwordx4 v[132:135], v217, s[0:1]
	global_load_dwordx4 v[164:167], v[136:137], off offset:2048
	global_load_dwordx4 v[160:163], v[136:137], off offset:3072
	global_load_dwordx4 v[172:175], v[136:137], off
	global_load_dwordx4 v[168:171], v[136:137], off offset:1024
	s_nop 0
	global_load_dwordx4 v[136:139], v218, s[0:1]
	global_load_dwordx4 v[140:143], v219, s[0:1]
	v_mov_b64_e32 v[186:187], v[184:185]
	v_mov_b64_e32 v[188:189], v[182:183]
	s_mov_b32 s30, s20
	s_add_i32 s21, s20, 0xf8
	s_waitcnt vmcnt(15)
	v_pk_add_f32 v[146:147], v[146:147], 1.0 op_sel_hi:[1,0]
	v_pk_add_f32 v[144:145], v[144:145], 1.0 op_sel_hi:[1,0]
	s_waitcnt vmcnt(14)
	v_pk_add_f32 v[150:151], v[150:151], 1.0 op_sel_hi:[1,0]
	v_pk_add_f32 v[148:149], v[148:149], 1.0 op_sel_hi:[1,0]
	s_waitcnt vmcnt(13)
	v_pk_add_f32 v[154:155], v[154:155], 1.0 op_sel_hi:[1,0]
	v_pk_add_f32 v[152:153], v[152:153], 1.0 op_sel_hi:[1,0]
	s_waitcnt vmcnt(10)
	v_pk_add_f32 v[224:225], v[192:193], 1.0 op_sel_hi:[1,0]
	v_pk_add_f32 v[226:227], v[190:191], 1.0 op_sel_hi:[1,0]
	v_pk_mul_f32 v[190:191], v[158:159], v[146:147]
	v_pk_mul_f32 v[192:193], v[156:157], v[144:145]
	v_pk_mul_f32 v[194:195], v[198:199], v[150:151]
	v_pk_mul_f32 v[196:197], v[196:197], v[148:149]
	s_waitcnt vmcnt(9)
	v_pk_mul_f32 v[198:199], v[202:203], v[154:155]
	v_pk_mul_f32 v[200:201], v[200:201], v[152:153]
	s_waitcnt vmcnt(4)
	v_mov_b64_e32 v[144:145], v[160:161]
	v_mov_b64_e32 v[148:149], v[164:165]
	s_waitcnt vmcnt(2)
	v_mov_b64_e32 v[152:153], v[168:169]
	v_mov_b64_e32 v[156:157], v[172:173]
	v_pk_mul_f32 v[202:203], v[206:207], v[224:225]
	v_pk_mul_f32 v[204:205], v[204:205], v[226:227]
	v_mov_b64_e32 v[146:147], v[162:163]
	v_mov_b64_e32 v[150:151], v[166:167]
	v_mov_b64_e32 v[154:155], v[170:171]
	v_mov_b64_e32 v[158:159], v[174:175]
	s_branch .LBB0_402
.LBB0_401:
	s_or_b64 exec, exec, s[36:37]
	s_waitcnt lgkmcnt(2)
	v_mov_b64_e32 v[162:163], v[146:147]
	s_waitcnt lgkmcnt(0)
	v_mov_b64_e32 v[166:167], v[150:151]
	v_mov_b64_e32 v[170:171], v[154:155]
	v_mov_b64_e32 v[174:175], v[158:159]
	v_lshl_add_u64 v[188:189], v[188:189], 0, s[100:101]
	v_lshl_add_u64 v[186:187], v[186:187], 0, s[28:29]
	s_and_b64 vcc, exec, s[34:35]
	v_mov_b64_e32 v[160:161], v[144:145]
	v_mov_b64_e32 v[164:165], v[148:149]
	v_mov_b64_e32 v[168:169], v[152:153]
	v_mov_b64_e32 v[172:173], v[156:157]
	s_cbranch_vccnz .LBB0_399
.LBB0_402:
	s_mov_b32 s0, s30
	s_add_i32 s30, s30, 8
	s_cmp_ge_i32 s0, s21
	s_cselect_b64 s[34:35], -1, 0
	s_cmp_lt_i32 s0, s21
	s_cbranch_scc0 .LBB0_404
	s_ashr_i32 s31, s30, 31
	s_lshl_b64 s[0:1], s[30:31], 12
	v_lshl_add_u64 v[144:145], v[176:177], 0, s[0:1]
	global_load_dwordx4 v[156:159], v[144:145], off
	global_load_dwordx4 v[152:155], v[144:145], off offset:1024
	global_load_dwordx4 v[148:151], v[144:145], off offset:2048
	s_nop 0
	global_load_dwordx4 v[144:147], v[144:145], off offset:3072

.LBB0_948:
	s_cmpk_lg_i32 s36, 0x400
	s_cbranch_scc1 .LBB0_947
	v_mov_b32_e32 v1, v198
	s_nop 0
	v_add_u32_e32 v1, s61, v1
	v_add_u32_e32 v2, s23, v1
	v_ashrrev_i32_e32 v3, 31, v2
	v_lshlrev_b64 v[2:3], 5, v[2:3]
	v_lshl_add_u64 v[2:3], s[44:45], 0, v[2:3]
	global_load_dwordx4 v[164:167], v[2:3], off
	global_load_dwordx4 v[168:171], v[2:3], off offset:16
	v_add_u32_e32 v2, s83, v1
	v_ashrrev_i32_e32 v3, 31, v2
	v_lshlrev_b64 v[2:3], 5, v[2:3]
	v_lshl_add_u64 v[2:3], s[44:45], 0, v[2:3]
	global_load_dwordx4 v[172:175], v[2:3], off
	global_load_dwordx4 v[176:179], v[2:3], off offset:16
	v_add_u32_e32 v2, s84, v1
	v_ashrrev_i32_e32 v3, 31, v2
	v_lshlrev_b64 v[2:3], 5, v[2:3]
	v_lshl_add_u64 v[2:3], s[44:45], 0, v[2:3]
	global_load_dwordx4 v[180:183], v[2:3], off
	global_load_dwordx4 v[184:187], v[2:3], off offset:16
	v_add_u32_e32 v2, s85, v1
	v_ashrrev_i32_e32 v3, 31, v2
	v_lshlrev_b64 v[2:3], 5, v[2:3]
	v_lshl_add_u64 v[2:3], s[44:45], 0, v[2:3]
	global_load_dwordx4 v[188:191], v[2:3], off
	global_load_dwordx4 v[192:195], v[2:3], off offset:16
	v_add_u32_e32 v2, s88, v1
	v_ashrrev_i32_e32 v3, 31, v2
	v_lshlrev_b64 v[2:3], 5, v[2:3]
	v_lshl_add_u64 v[2:3], s[44:45], 0, v[2:3]
	global_load_dwordx4 v[212:215], v[2:3], off
	global_load_dwordx4 v[216:219], v[2:3], off offset:16
	v_add_u32_e32 v2, s89, v1
	v_ashrrev_i32_e32 v3, 31, v2
	v_lshlrev_b64 v[2:3], 5, v[2:3]
	v_lshl_add_u64 v[2:3], s[44:45], 0, v[2:3]
	global_load_dwordx4 v[220:223], v[2:3], off
	global_load_dwordx4 v[224:227], v[2:3], off offset:16
	v_add_u32_e32 v2, s90, v1
	v_ashrrev_i32_e32 v3, 31, v2
	v_lshlrev_b64 v[2:3], 5, v[2:3]
	v_lshl_add_u64 v[2:3], s[44:45], 0, v[2:3]
	global_load_dwordx4 v[228:231], v[2:3], off
	global_load_dwordx4 v[232:235], v[2:3], off offset:16
	v_add_u32_e32 v2, s91, v1
	v_ashrrev_i32_e32 v3, 31, v2
	v_lshlrev_b64 v[2:3], 5, v[2:3]
	v_lshl_add_u64 v[2:3], s[44:45], 0, v[2:3]
	global_load_dwordx4 v[240:243], v[2:3], off
	global_load_dwordx4 v[236:239], v[2:3], off offset:16
	s_waitcnt vmcnt(0)
	v_mov_b32_e32 v2, v164
	v_mov_b32_e32 v3, v168
	v_mov_b32_e32 v168, v165
	v_mov_b32_e32 v164, v166
	v_mov_b32_e32 v165, v170
	v_mov_b32_e32 v170, v167
	v_pk_add_f32 v[2:3], v[2:3], v[168:169]
	v_pk_add_f32 v[164:165], v[164:165], v[170:171]
	s_nop 0
	v_pk_add_f32 v[2:3], v[2:3], v[164:165]
	s_nop 0
	v_add_f32_e32 v2, v2, v3
	v_fmamk_f32 v2, v2, 0x3b000000, v202
	v_cmp_gt_f32_e32 vcc, s77, v2
	v_mul_f32_e32 v3, 0x4f800000, v2
	s_nop 0
	v_cndmask_b32_e32 v2, v2, v3, vcc
	v_sqrt_f32_e32 v3, v2
	s_nop 0
	v_add_u32_e32 v164, -1, v3
	v_fma_f32 v165, -v164, v3, v2
	v_cmp_ge_f32_e64 s[0:1], 0, v165
	v_add_u32_e32 v165, 1, v3
	s_nop 0
	v_cndmask_b32_e64 v164, v3, v164, s[0:1]
	v_fma_f32 v3, -v165, v3, v2
	v_cmp_lt_f32_e64 s[0:1], 0, v3
	s_nop 1
	v_cndmask_b32_e64 v3, v164, v165, s[0:1]
	v_mul_f32_e32 v164, 0x37800000, v3
	v_cndmask_b32_e32 v3, v3, v164, vcc
	v_cmp_class_f32_e32 vcc, v2, v203
	s_nop 1
	v_cndmask_b32_e32 v2, v3, v2, vcc
	v_div_scale_f32 v3, s[0:1], v2, v2, 1.0
	v_rcp_f32_e32 v164, v3
	s_nop 0
	v_fma_f32 v165, -v3, v164, 1.0
	v_fmac_f32_e32 v164, v165, v164
	v_div_scale_f32 v165, vcc, 1.0, v2, 1.0
	v_mul_f32_e32 v166, v165, v164
	v_fma_f32 v167, -v3, v166, v165
	v_fmac_f32_e32 v166, v167, v164
	v_fma_f32 v3, -v3, v166, v165
	v_div_fmas_f32 v3, v3, v164, v166
	v_div_fixup_f32 v2, v3, v2, 1.0
	v_pk_mul_f32 v[122:123], v[122:123], v[2:3] op_sel_hi:[1,0]
	v_pk_mul_f32 v[120:121], v[120:121], v[2:3] op_sel_hi:[1,0]
	v_pk_mul_f32 v[130:131], v[130:131], v[2:3] op_sel_hi:[1,0]
	v_pk_mul_f32 v[128:129], v[128:129], v[2:3] op_sel_hi:[1,0]
	v_pk_mul_f32 v[126:127], v[126:127], v[2:3] op_sel_hi:[1,0]
	v_pk_mul_f32 v[124:125], v[124:125], v[2:3] op_sel_hi:[1,0]
	v_pk_mul_f32 v[118:119], v[118:119], v[2:3] op_sel_hi:[1,0]
	v_pk_mul_f32 v[116:117], v[116:117], v[2:3] op_sel_hi:[1,0]
	v_mov_b32_e32 v2, v172
	v_mov_b32_e32 v3, v176
	v_mov_b32_e32 v176, v173
	v_mov_b32_e32 v172, v174
	v_mov_b32_e32 v173, v178
	v_mov_b32_e32 v178, v175
	v_pk_add_f32 v[2:3], v[2:3], v[176:177]
	v_pk_add_f32 v[172:173], v[172:173], v[178:179]
	s_nop 0
	v_pk_add_f32 v[2:3], v[2:3], v[172:173]
	s_nop 0
	v_add_f32_e32 v2, v2, v3
	v_fmamk_f32 v2, v2, 0x3b000000, v202
	v_cmp_gt_f32_e32 vcc, s77, v2
	v_mul_f32_e32 v3, 0x4f800000, v2
	s_nop 0
	v_cndmask_b32_e32 v2, v2, v3, vcc
	v_sqrt_f32_e32 v3, v2
	s_nop 0
	v_add_u32_e32 v172, -1, v3
	v_fma_f32 v173, -v172, v3, v2
	v_cmp_ge_f32_e64 s[0:1], 0, v173
	v_add_u32_e32 v173, 1, v3
	s_nop 0
	v_cndmask_b32_e64 v172, v3, v172, s[0:1]
	v_fma_f32 v3, -v173, v3, v2
	v_cmp_lt_f32_e64 s[0:1], 0, v3
	s_nop 1
	v_cndmask_b32_e64 v3, v172, v173, s[0:1]
	v_mul_f32_e32 v172, 0x37800000, v3
	v_cndmask_b32_e32 v3, v3, v172, vcc
	v_cmp_class_f32_e32 vcc, v2, v203
	s_nop 1
	v_cndmask_b32_e32 v2, v3, v2, vcc
	v_div_scale_f32 v3, s[0:1], v2, v2, 1.0
	v_rcp_f32_e32 v172, v3
	s_nop 0
	v_fma_f32 v173, -v3, v172, 1.0
	v_fmac_f32_e32 v172, v173, v172
	v_div_scale_f32 v173, vcc, 1.0, v2, 1.0
	v_mul_f32_e32 v174, v173, v172
	v_fma_f32 v175, -v3, v174, v173
	v_fmac_f32_e32 v174, v175, v172
	v_fma_f32 v3, -v3, v174, v173
	v_div_fmas_f32 v3, v3, v172, v174
	v_div_fixup_f32 v2, v3, v2, 1.0
	v_pk_mul_f32 v[114:115], v[114:115], v[2:3] op_sel_hi:[1,0]
	v_pk_mul_f32 v[112:113], v[112:113], v[2:3] op_sel_hi:[1,0]
	v_pk_mul_f32 v[110:111], v[110:111], v[2:3] op_sel_hi:[1,0]
	v_pk_mul_f32 v[108:109], v[108:109], v[2:3] op_sel_hi:[1,0]
	v_pk_mul_f32 v[106:107], v[106:107], v[2:3] op_sel_hi:[1,0]
	v_pk_mul_f32 v[104:105], v[104:105], v[2:3] op_sel_hi:[1,0]
	v_pk_mul_f32 v[102:103], v[102:103], v[2:3] op_sel_hi:[1,0]
	v_pk_mul_f32 v[100:101], v[100:101], v[2:3] op_sel_hi:[1,0]
	v_mov_b32_e32 v2, v180
	v_mov_b32_e32 v3, v184
	v_mov_b32_e32 v184, v181
	v_mov_b32_e32 v180, v182
	v_mov_b32_e32 v181, v186
	v_mov_b32_e32 v186, v183
	v_pk_add_f32 v[2:3], v[2:3], v[184:185]
	v_pk_add_f32 v[180:181], v[180:181], v[186:187]
	s_nop 0
	v_pk_add_f32 v[2:3], v[2:3], v[180:181]
	s_nop 0
	v_add_f32_e32 v2, v2, v3
	v_fmamk_f32 v2, v2, 0x3b000000, v202
	v_cmp_gt_f32_e32 vcc, s77, v2
	v_mul_f32_e32 v3, 0x4f800000, v2
	s_nop 0
	v_cndmask_b32_e32 v2, v2, v3, vcc
	v_sqrt_f32_e32 v3, v2
	s_nop 0
	v_add_u32_e32 v180, -1, v3
	v_fma_f32 v181, -v180, v3, v2
	v_cmp_ge_f32_e64 s[0:1], 0, v181
	v_add_u32_e32 v181, 1, v3
	s_nop 0
	v_cndmask_b32_e64 v180, v3, v180, s[0:1]
	v_fma_f32 v3, -v181, v3, v2
	v_cmp_lt_f32_e64 s[0:1], 0, v3
	s_nop 1
	v_cndmask_b32_e64 v3, v180, v181, s[0:1]
	v_mul_f32_e32 v180, 0x37800000, v3
	v_cndmask_b32_e32 v3, v3, v180, vcc
	v_cmp_class_f32_e32 vcc, v2, v203
	s_nop 1
	v_cndmask_b32_e32 v2, v3, v2, vcc
	v_div_scale_f32 v3, s[0:1], v2, v2, 1.0
	v_rcp_f32_e32 v180, v3
	s_nop 0
	v_fma_f32 v181, -v3, v180, 1.0
	v_fmac_f32_e32 v180, v181, v180
	v_div_scale_f32 v181, vcc, 1.0, v2, 1.0
	v_mul_f32_e32 v182, v181, v180
	v_fma_f32 v183, -v3, v182, v181
	v_fmac_f32_e32 v182, v183, v180
	v_fma_f32 v3, -v3, v182, v181
	v_div_fmas_f32 v3, v3, v180, v182
	v_div_fixup_f32 v2, v3, v2, 1.0
	v_pk_mul_f32 v[98:99], v[98:99], v[2:3] op_sel_hi:[1,0]
	v_pk_mul_f32 v[96:97], v[96:97], v[2:3] op_sel_hi:[1,0]
	v_pk_mul_f32 v[94:95], v[94:95], v[2:3] op_sel_hi:[1,0]
	v_pk_mul_f32 v[92:93], v[92:93], v[2:3] op_sel_hi:[1,0]
	v_pk_mul_f32 v[90:91], v[90:91], v[2:3] op_sel_hi:[1,0]
	v_pk_mul_f32 v[88:89], v[88:89], v[2:3] op_sel_hi:[1,0]
	v_pk_mul_f32 v[86:87], v[86:87], v[2:3] op_sel_hi:[1,0]
	v_pk_mul_f32 v[84:85], v[84:85], v[2:3] op_sel_hi:[1,0]
	v_mov_b32_e32 v2, v188
	v_mov_b32_e32 v3, v192
	v_mov_b32_e32 v192, v189
	v_mov_b32_e32 v188, v190
	v_mov_b32_e32 v189, v194
	v_mov_b32_e32 v194, v191
	v_pk_add_f32 v[2:3], v[2:3], v[192:193]
	v_pk_add_f32 v[188:189], v[188:189], v[194:195]
	s_nop 0
	v_pk_add_f32 v[2:3], v[2:3], v[188:189]
	s_nop 0
	v_add_f32_e32 v2, v2, v3
	v_fmamk_f32 v2, v2, 0x3b000000, v202
	v_cmp_gt_f32_e32 vcc, s77, v2
	v_mul_f32_e32 v3, 0x4f800000, v2
	s_nop 0
	v_cndmask_b32_e32 v2, v2, v3, vcc
	v_sqrt_f32_e32 v3, v2
	s_nop 0
	v_add_u32_e32 v188, -1, v3
	v_fma_f32 v189, -v188, v3, v2
	v_cmp_ge_f32_e64 s[0:1], 0, v189
	v_add_u32_e32 v189, 1, v3
	s_nop 0
	v_cndmask_b32_e64 v188, v3, v188, s[0:1]
	v_fma_f32 v3, -v189, v3, v2
	v_cmp_lt_f32_e64 s[0:1], 0, v3
	s_nop 1
	v_cndmask_b32_e64 v3, v188, v189, s[0:1]
	v_mul_f32_e32 v188, 0x37800000, v3
	v_cndmask_b32_e32 v3, v3, v188, vcc
	v_cmp_class_f32_e32 vcc, v2, v203
	s_nop 1
	v_cndmask_b32_e32 v2, v3, v2, vcc
	v_div_scale_f32 v3, s[0:1], v2, v2, 1.0
	v_rcp_f32_e32 v188, v3
	s_nop 0
	v_fma_f32 v189, -v3, v188, 1.0
	v_fmac_f32_e32 v188, v189, v188
	v_div_scale_f32 v189, vcc, 1.0, v2, 1.0
	v_mul_f32_e32 v190, v189, v188
	v_fma_f32 v191, -v3, v190, v189
	v_fmac_f32_e32 v190, v191, v188
	v_fma_f32 v3, -v3, v190, v189
	v_div_fmas_f32 v3, v3, v188, v190
	v_div_fixup_f32 v2, v3, v2, 1.0
	v_pk_mul_f32 v[82:83], v[82:83], v[2:3] op_sel_hi:[1,0]
	v_pk_mul_f32 v[80:81], v[80:81], v[2:3] op_sel_hi:[1,0]
	v_pk_mul_f32 v[78:79], v[78:79], v[2:3] op_sel_hi:[1,0]
	v_pk_mul_f32 v[76:77], v[76:77], v[2:3] op_sel_hi:[1,0]
	v_pk_mul_f32 v[74:75], v[74:75], v[2:3] op_sel_hi:[1,0]
	v_pk_mul_f32 v[72:73], v[72:73], v[2:3] op_sel_hi:[1,0]
	v_pk_mul_f32 v[70:71], v[70:71], v[2:3] op_sel_hi:[1,0]
	v_pk_mul_f32 v[68:69], v[68:69], v[2:3] op_sel_hi:[1,0]
	v_mov_b32_e32 v2, v212
	v_mov_b32_e32 v3, v216
	v_mov_b32_e32 v216, v213
	v_mov_b32_e32 v212, v214
	v_mov_b32_e32 v213, v218
	v_mov_b32_e32 v218, v215
	v_pk_add_f32 v[2:3], v[2:3], v[216:217]
	v_pk_add_f32 v[212:213], v[212:213], v[218:219]
	s_nop 0
	v_pk_add_f32 v[2:3], v[2:3], v[212:213]
	s_nop 0
	v_add_f32_e32 v2, v2, v3
	v_fmamk_f32 v2, v2, 0x3b000000, v202
	v_cmp_gt_f32_e32 vcc, s77, v2
	v_mul_f32_e32 v3, 0x4f800000, v2
	s_nop 0
	v_cndmask_b32_e32 v2, v2, v3, vcc
	v_sqrt_f32_e32 v3, v2
	s_nop 0
	v_add_u32_e32 v212, -1, v3
	v_fma_f32 v213, -v212, v3, v2
	v_cmp_ge_f32_e64 s[0:1], 0, v213
	v_add_u32_e32 v213, 1, v3
	s_nop 0
	v_cndmask_b32_e64 v212, v3, v212, s[0:1]
	v_fma_f32 v3, -v213, v3, v2
	v_cmp_lt_f32_e64 s[0:1], 0, v3
	s_nop 1
	v_cndmask_b32_e64 v3, v212, v213, s[0:1]
	v_mul_f32_e32 v212, 0x37800000, v3
	v_cndmask_b32_e32 v3, v3, v212, vcc
	v_cmp_class_f32_e32 vcc, v2, v203
	s_nop 1
	v_cndmask_b32_e32 v2, v3, v2, vcc
	v_div_scale_f32 v3, s[0:1], v2, v2, 1.0
	v_rcp_f32_e32 v212, v3
	s_nop 0
	v_fma_f32 v213, -v3, v212, 1.0
	v_fmac_f32_e32 v212, v213, v212
	v_div_scale_f32 v213, vcc, 1.0, v2, 1.0
	v_mul_f32_e32 v214, v213, v212
	v_fma_f32 v215, -v3, v214, v213
	v_fmac_f32_e32 v214, v215, v212
	v_fma_f32 v3, -v3, v214, v213
	v_div_fmas_f32 v3, v3, v212, v214
	v_div_fixup_f32 v2, v3, v2, 1.0
	v_pk_mul_f32 v[66:67], v[66:67], v[2:3] op_sel_hi:[1,0]
	v_pk_mul_f32 v[64:65], v[64:65], v[2:3] op_sel_hi:[1,0]
	v_pk_mul_f32 v[62:63], v[62:63], v[2:3] op_sel_hi:[1,0]
	v_pk_mul_f32 v[60:61], v[60:61], v[2:3] op_sel_hi:[1,0]
	v_pk_mul_f32 v[58:59], v[58:59], v[2:3] op_sel_hi:[1,0]
	v_pk_mul_f32 v[56:57], v[56:57], v[2:3] op_sel_hi:[1,0]
	v_pk_mul_f32 v[54:55], v[54:55], v[2:3] op_sel_hi:[1,0]
	v_pk_mul_f32 v[52:53], v[52:53], v[2:3] op_sel_hi:[1,0]
	v_mov_b32_e32 v2, v220
	v_mov_b32_e32 v3, v224
	v_mov_b32_e32 v224, v221
	v_mov_b32_e32 v220, v222
	v_mov_b32_e32 v221, v226
	v_mov_b32_e32 v226, v223
	v_pk_add_f32 v[2:3], v[2:3], v[224:225]
	v_pk_add_f32 v[220:221], v[220:221], v[226:227]
	s_nop 0
	v_pk_add_f32 v[2:3], v[2:3], v[220:221]
	s_nop 0
	v_add_f32_e32 v2, v2, v3
	v_fmamk_f32 v2, v2, 0x3b000000, v202
	v_cmp_gt_f32_e32 vcc, s77, v2
	v_mul_f32_e32 v3, 0x4f800000, v2
	s_nop 0
	v_cndmask_b32_e32 v2, v2, v3, vcc
	v_sqrt_f32_e32 v3, v2
	s_nop 0
	v_add_u32_e32 v220, -1, v3
	v_fma_f32 v221, -v220, v3, v2
	v_cmp_ge_f32_e64 s[0:1], 0, v221
	v_add_u32_e32 v221, 1, v3
	s_nop 0
	v_cndmask_b32_e64 v220, v3, v220, s[0:1]
	v_fma_f32 v3, -v221, v3, v2
	v_cmp_lt_f32_e64 s[0:1], 0, v3
	s_nop 1
	v_cndmask_b32_e64 v3, v220, v221, s[0:1]
	v_mul_f32_e32 v220, 0x37800000, v3
	v_cndmask_b32_e32 v3, v3, v220, vcc
	v_cmp_class_f32_e32 vcc, v2, v203
	s_nop 1
	v_cndmask_b32_e32 v2, v3, v2, vcc
	v_div_scale_f32 v3, s[0:1], v2, v2, 1.0
	v_rcp_f32_e32 v220, v3
	s_nop 0
	v_fma_f32 v221, -v3, v220, 1.0
	v_fmac_f32_e32 v220, v221, v220
	v_div_scale_f32 v221, vcc, 1.0, v2, 1.0
	v_mul_f32_e32 v222, v221, v220
	v_fma_f32 v223, -v3, v222, v221
	v_fmac_f32_e32 v222, v223, v220
	v_fma_f32 v3, -v3, v222, v221
	v_div_fmas_f32 v3, v3, v220, v222
	v_div_fixup_f32 v2, v3, v2, 1.0
	v_pk_mul_f32 v[50:51], v[50:51], v[2:3] op_sel_hi:[1,0]
	v_pk_mul_f32 v[48:49], v[48:49], v[2:3] op_sel_hi:[1,0]
	v_pk_mul_f32 v[46:47], v[46:47], v[2:3] op_sel_hi:[1,0]
	v_pk_mul_f32 v[44:45], v[44:45], v[2:3] op_sel_hi:[1,0]
	v_pk_mul_f32 v[42:43], v[42:43], v[2:3] op_sel_hi:[1,0]
	v_pk_mul_f32 v[40:41], v[40:41], v[2:3] op_sel_hi:[1,0]
	v_pk_mul_f32 v[38:39], v[38:39], v[2:3] op_sel_hi:[1,0]
	v_pk_mul_f32 v[36:37], v[36:37], v[2:3] op_sel_hi:[1,0]
	v_mov_b32_e32 v2, v228
	v_mov_b32_e32 v3, v232
	v_mov_b32_e32 v232, v229
	v_mov_b32_e32 v228, v230
	v_mov_b32_e32 v229, v234
	v_mov_b32_e32 v234, v231
	v_pk_add_f32 v[2:3], v[2:3], v[232:233]
	v_pk_add_f32 v[228:229], v[228:229], v[234:235]
	s_nop 0
	v_pk_add_f32 v[2:3], v[2:3], v[228:229]
	s_nop 0
	v_add_f32_e32 v2, v2, v3
	v_fmamk_f32 v2, v2, 0x3b000000, v202
	v_cmp_gt_f32_e32 vcc, s77, v2
	v_mul_f32_e32 v3, 0x4f800000, v2
	s_nop 0
	v_cndmask_b32_e32 v2, v2, v3, vcc
	v_sqrt_f32_e32 v3, v2
	s_nop 0
	v_add_u32_e32 v228, -1, v3
	v_fma_f32 v229, -v228, v3, v2
	v_cmp_ge_f32_e64 s[0:1], 0, v229
	v_add_u32_e32 v229, 1, v3
	s_nop 0
	v_cndmask_b32_e64 v228, v3, v228, s[0:1]
	v_fma_f32 v3, -v229, v3, v2
	v_cmp_lt_f32_e64 s[0:1], 0, v3
	s_nop 1
	v_cndmask_b32_e64 v3, v228, v229, s[0:1]
	v_mul_f32_e32 v228, 0x37800000, v3
	v_cndmask_b32_e32 v3, v3, v228, vcc
	v_cmp_class_f32_e32 vcc, v2, v203
	s_nop 1
	v_cndmask_b32_e32 v2, v3, v2, vcc
	v_div_scale_f32 v3, s[0:1], v2, v2, 1.0
	v_rcp_f32_e32 v228, v3
	s_nop 0
	v_fma_f32 v229, -v3, v228, 1.0
	v_fmac_f32_e32 v228, v229, v228
	v_div_scale_f32 v229, vcc, 1.0, v2, 1.0
	v_mul_f32_e32 v230, v229, v228
	v_fma_f32 v231, -v3, v230, v229
	v_fmac_f32_e32 v230, v231, v228
	v_fma_f32 v3, -v3, v230, v229
	v_div_fmas_f32 v3, v3, v228, v230
	v_div_fixup_f32 v2, v3, v2, 1.0
	v_pk_mul_f32 v[34:35], v[34:35], v[2:3] op_sel_hi:[1,0]
	v_pk_mul_f32 v[32:33], v[32:33], v[2:3] op_sel_hi:[1,0]
	v_pk_mul_f32 v[30:31], v[30:31], v[2:3] op_sel_hi:[1,0]
	v_pk_mul_f32 v[28:29], v[28:29], v[2:3] op_sel_hi:[1,0]
	v_pk_mul_f32 v[26:27], v[26:27], v[2:3] op_sel_hi:[1,0]
	v_pk_mul_f32 v[24:25], v[24:25], v[2:3] op_sel_hi:[1,0]
	v_pk_mul_f32 v[22:23], v[22:23], v[2:3] op_sel_hi:[1,0]
	v_pk_mul_f32 v[20:21], v[20:21], v[2:3] op_sel_hi:[1,0]
	v_mov_b32_e32 v2, v240
	v_mov_b32_e32 v3, v236
	v_mov_b32_e32 v236, v241
	v_pk_add_f32 v[2:3], v[2:3], v[236:237]
	v_mov_b32_e32 v236, v242
	v_mov_b32_e32 v237, v238
	v_mov_b32_e32 v238, v243
	v_pk_add_f32 v[236:237], v[236:237], v[238:239]
	s_nop 0
	v_pk_add_f32 v[2:3], v[2:3], v[236:237]
	s_nop 0
	v_add_f32_e32 v1, v2, v3
	v_fmamk_f32 v1, v1, 0x3b000000, v202
	v_cmp_gt_f32_e32 vcc, s77, v1
	v_mul_f32_e32 v2, 0x4f800000, v1
	s_nop 0
	v_cndmask_b32_e32 v1, v1, v2, vcc
	v_sqrt_f32_e32 v2, v1
	s_nop 0
	v_add_u32_e32 v3, -1, v2
	v_fma_f32 v236, -v3, v2, v1
	v_cmp_ge_f32_e64 s[0:1], 0, v236
	v_add_u32_e32 v236, 1, v2
	s_nop 0
	v_cndmask_b32_e64 v3, v2, v3, s[0:1]
	v_fma_f32 v2, -v236, v2, v1
	v_cmp_lt_f32_e64 s[0:1], 0, v2
	s_nop 1
	v_cndmask_b32_e64 v2, v3, v236, s[0:1]
	v_mul_f32_e32 v3, 0x37800000, v2
	v_cndmask_b32_e32 v2, v2, v3, vcc
	v_cmp_class_f32_e32 vcc, v1, v203
	s_nop 1
	v_cndmask_b32_e32 v1, v2, v1, vcc
	v_div_scale_f32 v2, s[0:1], v1, v1, 1.0
	v_rcp_f32_e32 v3, v2
	s_nop 0
	v_fma_f32 v236, -v2, v3, 1.0
	v_fmac_f32_e32 v3, v236, v3
	v_div_scale_f32 v236, vcc, 1.0, v1, 1.0
	v_mul_f32_e32 v237, v236, v3
	v_fma_f32 v238, -v2, v237, v236
	v_fmac_f32_e32 v237, v238, v3
	v_fma_f32 v2, -v2, v237, v236
	v_div_fmas_f32 v2, v2, v3, v237
	v_div_fixup_f32 v2, v2, v1, 1.0
	v_pk_mul_f32 v[18:19], v[18:19], v[2:3] op_sel_hi:[1,0]
	v_pk_mul_f32 v[16:17], v[16:17], v[2:3] op_sel_hi:[1,0]
	v_pk_mul_f32 v[14:15], v[14:15], v[2:3] op_sel_hi:[1,0]
	v_pk_mul_f32 v[12:13], v[12:13], v[2:3] op_sel_hi:[1,0]
	v_pk_mul_f32 v[10:11], v[10:11], v[2:3] op_sel_hi:[1,0]
	v_pk_mul_f32 v[8:9], v[8:9], v[2:3] op_sel_hi:[1,0]
	v_pk_mul_f32 v[6:7], v[6:7], v[2:3] op_sel_hi:[1,0]
	v_pk_mul_f32 v[4:5], v[4:5], v[2:3] op_sel_hi:[1,0]
	s_branch .LBB0_947
